# prep unit k-mean partial sums: LDS reads issued back to back instead of 16 dependent round trips
# baseline (speedup 1.0000x reference)
; #define BAR_LDS() do { asm volatile("s_waitcnt lgkmcnt(0)" ::: "memory"); __builtin_amdgcn_s_barrier(); asm volatile("" ::: "memory"); } while (0)
; __device__ __forceinline__ void moba_prep_unit(const Args& a, int l, LAS unsigned char* lds, int tid, int u, const PrepIn& in, PrepIn& nxt, int unext) {
;     ...
;         const int d = tid & 63, pt = tid >> 6; float sacc = 0.f;
; #pragma unroll 8
;         for (int t = 0; t < 32; ++t) sacc += kt[(pt * 32 + t) * 65 + d];
;         part[pt * 64 + d] = sacc;
;     }
;     BAR_LDS();
;     if (tid < 64) { float sacc = 0.f;
; #pragma unroll
;         for (int p = 0; p < 8; ++p) sacc += part[p * 64 + tid];
;         ((float*)(a.ws + WS_KMEAN))[((size_t)(b * 8 + h) * 8 + j) * 64 + tid] = sacc * (1.f / 256.f); }
.LBB0_432:
	v_add_u32_e32 v52, 0x0, v127
	ds_read2_b32 v[54:55], v52 offset1:65
	ds_read2_b32 v[56:57], v52 offset0:130 offset1:195
	v_add_u32_e32 v51, 0x400, v127
	ds_read2_b32 v[58:59], v51 offset0:4 offset1:69
	ds_read2_b32 v[60:61], v51 offset0:134 offset1:199
	v_add_u32_e32 v52, 0x820, v127
	ds_read2_b32 v[62:63], v52 offset1:65
	ds_read2_b32 v[64:65], v52 offset0:130 offset1:195
	v_add_u32_e32 v51, 0xc20, v127
	ds_read2_b32 v[66:67], v51 offset0:4 offset1:69
	ds_read2_b32 v[68:69], v51 offset0:134 offset1:199
	v_add_u32_e32 v52, 0x1040, v127
	ds_read2_b32 v[70:71], v52 offset1:65
	ds_read2_b32 v[72:73], v52 offset0:130 offset1:195
	v_add_u32_e32 v51, 0x1440, v127
	ds_read2_b32 v[74:75], v51 offset0:4 offset1:69
	ds_read2_b32 v[76:77], v51 offset0:134 offset1:199
	s_waitcnt lgkmcnt(11)
	v_add_f32_e32 v48, v48, v54
	v_add_f32_e32 v48, v48, v55
	v_add_u32_e32 v52, 0x1860, v127
	ds_read2_b32 v[78:79], v52 offset1:65
	s_waitcnt lgkmcnt(11)
	v_add_f32_e32 v48, v48, v56
	v_add_f32_e32 v48, v48, v57
	ds_read2_b32 v[80:81], v52 offset0:130 offset1:195
	s_waitcnt lgkmcnt(11)
	v_add_f32_e32 v48, v48, v58
	v_add_f32_e32 v48, v48, v59
	v_add_u32_e32 v51, 0x1c60, v127
	ds_read2_b32 v[82:83], v51 offset0:4 offset1:69
	s_waitcnt lgkmcnt(11)
	v_add_f32_e32 v48, v48, v60
	v_add_f32_e32 v48, v48, v61
	ds_read2_b32 v[84:85], v51 offset0:134 offset1:199
	s_waitcnt lgkmcnt(11)
	v_add_f32_e32 v48, v48, v62
	v_add_f32_e32 v48, v48, v63
	s_waitcnt lgkmcnt(10)
	v_add_f32_e32 v48, v48, v64
	v_add_f32_e32 v48, v48, v65
	s_waitcnt lgkmcnt(9)
	v_add_f32_e32 v48, v48, v66
	v_add_f32_e32 v48, v48, v67
	s_waitcnt lgkmcnt(8)
	v_add_f32_e32 v48, v48, v68
	v_add_f32_e32 v48, v48, v69
	s_waitcnt lgkmcnt(7)
	v_add_f32_e32 v48, v48, v70
	v_add_f32_e32 v48, v48, v71
	s_waitcnt lgkmcnt(6)
	v_add_f32_e32 v48, v48, v72
	v_add_f32_e32 v48, v48, v73
	s_waitcnt lgkmcnt(5)
	v_add_f32_e32 v48, v48, v74
	v_add_f32_e32 v48, v48, v75
	s_waitcnt lgkmcnt(4)
	v_add_f32_e32 v48, v48, v76
	v_add_f32_e32 v48, v48, v77
	s_waitcnt lgkmcnt(3)
	v_add_f32_e32 v48, v48, v78
	v_add_f32_e32 v48, v48, v79
	s_waitcnt lgkmcnt(2)
	v_add_f32_e32 v48, v48, v80
	v_add_f32_e32 v48, v48, v81
	s_waitcnt lgkmcnt(1)
	v_add_f32_e32 v48, v48, v82
	v_add_f32_e32 v48, v48, v83
	s_waitcnt lgkmcnt(0)
	v_add_f32_e32 v48, v48, v84
	v_add_f32_e32 v48, v48, v85
	ds_write_b32 v126, v48
	s_waitcnt lgkmcnt(0)
	s_barrier
	s_and_saveexec_b64 s[16:17], s[46:47]
	s_cbranch_execz .LBB0_426
	ds_read2st64_b32 v[54:55], v126 offset1:1
	ds_read2st64_b32 v[56:57], v126 offset0:2 offset1:3
	ds_read2st64_b32 v[58:59], v126 offset0:4 offset1:5
	ds_read2st64_b32 v[60:61], v126 offset0:6 offset1:7
	s_lshl_b64 s[8:9], s[14:15], 11
	v_readlane_b32 s5, v245, 42
	s_add_u32 s5, s5, s8
	v_readlane_b32 s8, v245, 43
	s_addc_u32 s9, s8, s9
	s_add_u32 s8, s5, s6
	s_addc_u32 s9, s9, 0
	s_waitcnt lgkmcnt(3)
	v_add_f32_e32 v48, 0, v54
	v_add_f32_e32 v48, v48, v55
	s_waitcnt lgkmcnt(2)
	v_add_f32_e32 v48, v48, v56
	v_add_f32_e32 v48, v48, v57
	s_waitcnt lgkmcnt(1)
	v_add_f32_e32 v48, v48, v58
	v_add_f32_e32 v48, v48, v59
	s_waitcnt lgkmcnt(0)
	v_add_f32_e32 v48, v48, v60
	v_add_f32_e32 v48, v48, v61
	v_mul_f32_e32 v50, 0x3b800000, v48
	v_lshl_add_u64 v[48:49], v[96:97], 2, s[8:9]
	global_store_dword v[48:49], v50, off
	s_branch .LBB0_426
